# v4 + MLA loop DMA via SGPR base/32-bit VGPR offset (no 64-bit VALU adds) + removed never-blocking lgkmcnt waits inside MFMA runs
# speedup vs baseline: 1.0089x; 1.0089x over previous
; DI int v_rd_base(int lane) { return ((lane & 3) << 3) | (((lane >> 2) & 3) << 6) | (((lane >> 4) & 1) << 5) | (((lane >> 5) & 1) << 8); }
; DI void expsum(f32x16& p, float& l_reg, bf16x8& pa0, bf16x8& pa1) {
; #pragma unroll
;     for (int r = 0; r < 16; ++r) p[r] = __builtin_amdgcn_exp2f(p[r]);
;     float ps = 0.f;
; #pragma unroll
;     for (int r = 0; r < 16; ++r) ps += p[r];
;     l_reg += ps; asm volatile("" : "+v"(l_reg));
;     ...
;     ATT_PK4(p, 0, pa0); ATT_PK4(p, 8, pa1);
; template <int DQK, int MODE, int LDQ, int LDK, int LDV> ...
;     ...
;     const int vbase = (int)(unsigned)(size_t)lds + V_OFF + v_rd_base(lane);
;     ...
;     constexpr int NDA = ND0 > 6 ? 6 : ND0;
.LBB0_1922:
	s_add_i32 s3, s0, -1
	s_add_i32 s2, s22, 0xffffa000
	s_and_b32 s2, s2, 0x6000
	v_add_u32_e32 v121, s2, v114
	v_add_u32_e32 v122, v121, v115
	v_add_u32_e32 v126, v121, v116
	ds_read_b128 v[122:125], v122 offset:4096
	ds_read_b128 v[132:135], v126 offset:4096
	v_add_u32_e32 v126, v121, v117
	v_add_u32_e32 v121, v121, v118
	s_lshl_b32 s2, s1, 14
	ds_read_b128 v[136:139], v126 offset:4096
	ds_read_b128 v[140:143], v121 offset:4096
	v_add_u32_e32 v121, s2, v106
	ds_read_b64_tr_b16 v[144:145], v121 offset:0
	ds_read_b64_tr_b16 v[146:147], v121 offset:0x800
	ds_read_b64_tr_b16 v[148:149], v121 offset:0x1000
	ds_read_b64_tr_b16 v[150:151], v121 offset:0x1800
	ds_read_b64_tr_b16 v[152:153], v121 offset:0x200
	ds_read_b64_tr_b16 v[154:155], v121 offset:0xa00
	ds_read_b64_tr_b16 v[156:157], v121 offset:0x1200
	ds_read_b64_tr_b16 v[158:159], v121 offset:0x1a00
	ds_read_b64_tr_b16 v[162:163], v121 offset:0x400
	ds_read_b64_tr_b16 v[164:165], v121 offset:0xc00
	ds_read_b64_tr_b16 v[166:167], v121 offset:0x1400
	ds_read_b64_tr_b16 v[168:169], v121 offset:0x1c00
	ds_read_b64_tr_b16 v[170:171], v121 offset:0x600
	ds_read_b64_tr_b16 v[172:173], v121 offset:0xe00
	ds_read_b64_tr_b16 v[174:175], v121 offset:0x1600
	ds_read_b64_tr_b16 v[176:177], v121 offset:0x1e00
	s_setprio 1
	v_exp_f32_e32 v64, v64
	v_exp_f32_e32 v65, v65
	v_exp_f32_e32 v66, v66
	v_exp_f32_e32 v67, v67
	v_exp_f32_e32 v68, v68
	v_add_f32_e32 v126, 0, v64
	v_exp_f32_e32 v69, v69
	v_add_f32_e32 v126, v65, v126
	v_exp_f32_e32 v70, v70
	v_add_f32_e32 v126, v66, v126
	v_exp_f32_e32 v71, v71
	v_add_f32_e32 v126, v67, v126
	v_exp_f32_e32 v72, v72
	v_add_f32_e32 v126, v68, v126
	v_exp_f32_e32 v73, v73
	v_add_f32_e32 v126, v69, v126
	v_exp_f32_e32 v74, v74
	v_add_f32_e32 v126, v70, v126
	v_exp_f32_e32 v75, v75
	v_add_f32_e32 v126, v71, v126
	v_exp_f32_e32 v76, v76
	v_add_f32_e32 v126, v72, v126
	v_exp_f32_e32 v77, v77
	v_add_f32_e32 v126, v73, v126
	v_exp_f32_e32 v78, v78
	v_add_f32_e32 v126, v74, v126
	v_exp_f32_e32 v79, v79
	v_add_f32_e32 v126, v75, v126
	v_add_f32_e32 v126, v76, v126
	v_add_f32_e32 v126, v77, v126
	v_add_f32_e32 v126, v78, v126
	v_add_f32_e32 v126, v79, v126
	v_add_f32_e32 v120, v126, v120
	v_cvt_pk_bf16_f32 v64, v64, v65
	v_cvt_pk_bf16_f32 v65, v66, v67
	v_cvt_pk_bf16_f32 v66, v68, v69
	v_cvt_pk_bf16_f32 v67, v70, v71
	v_cvt_pk_bf16_f32 v68, v72, v73
	v_cvt_pk_bf16_f32 v69, v74, v75
	v_cvt_pk_bf16_f32 v70, v76, v77
	v_cvt_pk_bf16_f32 v71, v78, v79
	s_nop 0
	v_permlane32_swap_b32_e32 v64, v66
	v_permlane32_swap_b32_e32 v65, v67
	v_permlane32_swap_b32_e32 v68, v70
	v_permlane32_swap_b32_e32 v69, v71
	s_waitcnt lgkmcnt(0)
	s_setprio 0
	v_mfma_f32_32x32x16_bf16 v[0:15], v[64:67], v[144:147], v[0:15]
	s_cmp_lt_i32 s3, s55
	s_cselect_b64 vcc, -1, 0
	s_cmp_ge_i32 s3, s97
	s_cselect_b64 s[74:75], -1, 0
	s_or_b64 s[74:75], vcc, s[74:75]
	s_and_b64 vcc, exec, s[74:75]
	v_mfma_f32_32x32x16_bf16 v[48:63], v[64:67], v[152:155], v[48:63]
	v_mfma_f32_32x32x16_bf16 v[32:47], v[64:67], v[162:165], v[32:47]
	v_mfma_f32_32x32x16_bf16 v[16:31], v[64:67], v[170:173], v[16:31]
	v_mfma_f32_32x32x16_bf16 v[0:15], v[68:71], v[148:151], v[0:15]
	v_mfma_f32_32x32x16_bf16 v[48:63], v[68:71], v[156:159], v[48:63]
	v_mfma_f32_32x32x16_bf16 v[32:47], v[68:71], v[166:169], v[32:47]
	v_mfma_f32_32x32x16_bf16 v[16:31], v[68:71], v[174:177], v[16:31]
	v_mfma_f32_32x32x16_bf16 v[64:79], v[122:125], v[92:95], 0
	v_mfma_f32_32x32x16_bf16 v[64:79], v[132:135], v[88:91], v[64:79]
	v_mfma_f32_32x32x16_bf16 v[64:79], v[136:139], v[84:87], v[64:79]
	v_mfma_f32_32x32x16_bf16 v[64:79], v[140:143], v[80:83], v[64:79]
	v_add_u32_e32 v122, s7, v119
	s_cbranch_vccnz .LBB0_1924
	v_add_u32_e32 v138, 0x28908, v122
	v_add_u32_e32 v140, 0x28920, v122
	v_add_u32_e32 v142, 0x28928, v122
	v_add_u32_e32 v124, 0x28940, v122
	v_add_u32_e32 v126, 0x28948, v122
	v_add_u32_e32 v132, 0x28960, v122
	v_add_u32_e32 v134, 0x28968, v122
	v_add_u32_e32 v123, 0x28900, v122
	ds_read2_b32 v[124:125], v124 offset1:1
	ds_read2_b32 v[126:127], v126 offset1:1
	ds_read2_b32 v[132:133], v132 offset1:1
	ds_read2_b32 v[134:135], v134 offset1:1
	ds_read2_b32 v[136:137], v123 offset1:1
	ds_read2_b32 v[138:139], v138 offset1:1
	ds_read2_b32 v[140:141], v140 offset1:1
	ds_read2_b32 v[142:143], v142 offset1:1
	s_waitcnt lgkmcnt(0)
	v_pk_add_f32 v[78:79], v[78:79], v[134:135]
	v_pk_add_f32 v[76:77], v[76:77], v[132:133]
	v_pk_add_f32 v[74:75], v[74:75], v[126:127]
	v_pk_add_f32 v[72:73], v[72:73], v[124:125]
	v_pk_add_f32 v[70:71], v[70:71], v[142:143]
	v_pk_add_f32 v[68:69], v[68:69], v[140:141]
	v_pk_add_f32 v[66:67], v[66:67], v[138:139]
	v_pk_add_f32 v[64:65], v[64:65], v[136:137]

; #define LAS __attribute__((address_space(3)))
; DI int v_rd_base(int lane) { return ((lane & 3) << 3) | (((lane >> 2) & 3) << 6) | (((lane >> 4) & 1) << 5) | (((lane >> 5) & 1) << 8); }
; DI void pv_mma(f32x16* o, const s16x4* vf, bf16x8 pa0, bf16x8 pa1) {
;     ...
; #pragma unroll
;     for (int d0 = 0; d0 < 4; ++d0) {
;         o[d0] = __builtin_amdgcn_mfma_f32_32x32x16_bf16(pa0, ATT_PK(vf[4 * d0], vf[4 * d0 + 1]), o[d0], 0, 0, 0);
;         o[d0] = __builtin_amdgcn_mfma_f32_32x32x16_bf16(pa1, ATT_PK(vf[4 * d0 + 2], vf[4 * d0 + 3]), o[d0], 0, 0, 0); }
;     ...
; }
; template <int DQK, int D0A, int D0B> DI void k_reads(bf16x8* kf, const LAS unsigned char* Ks, int half, int r32, int hi) {
; #pragma unroll
;     for (int d0 = D0A; d0 < D0B; ++d0) kf[d0 - D0A] = *(const LAS bf16x8*)(Ks + half * (32 * DQK * 2) + kswz<DQK>(r32, (d0 * 16 + hi * 8) * 2));
; }
; template <int D0A, int D0B> DI void qk_mma(f32x16& p, const bf16x8* kf, const bf16x8* qr) {
; #pragma unroll
;     for (int d0 = D0A; d0 < D0B; ++d0) {
;         if (d0 == 0) { f32x16 z; _Pragma("unroll") for (int r = 0; r < 16; ++r) z[r] = 0.f; p = __builtin_amdgcn_mfma_f32_32x32x16_bf16(kf[0], qr[0], z, 0, 0, 0); }
;         else p = __builtin_amdgcn_mfma_f32_32x32x16_bf16(kf[d0 - D0A], qr[d0], p, 0, 0, 0); }
; }
; template <int DQK, int MODE, int LDQ, int LDK, int LDV> ...
;     ...
;     const int vbase = (int)(unsigned)(size_t)lds + V_OFF + v_rd_base(lane);
;     ...
;     constexpr int NDA = ND0 > 6 ? 6 : ND0;
.Lstg_d0_mid_11:
	v_mfma_f32_32x32x16_bf16 v[0:15], v[64:67], v[144:147], v[0:15]
	s_cmp_lt_i32 s0, s55
	s_cselect_b64 s[74:75], -1, 0
	s_cmp_ge_i32 s0, s97
	s_cselect_b64 vcc, -1, 0
	s_or_b64 s[74:75], s[74:75], vcc
	s_and_b64 vcc, exec, s[74:75]
	v_mfma_f32_32x32x16_bf16 v[48:63], v[64:67], v[152:155], v[48:63]
	v_mfma_f32_32x32x16_bf16 v[32:47], v[64:67], v[162:165], v[32:47]
	v_mfma_f32_32x32x16_bf16 v[16:31], v[64:67], v[170:173], v[16:31]
	v_mfma_f32_32x32x16_bf16 v[0:15], v[68:71], v[148:151], v[0:15]
	v_mfma_f32_32x32x16_bf16 v[48:63], v[68:71], v[156:159], v[48:63]
	v_mfma_f32_32x32x16_bf16 v[32:47], v[68:71], v[166:169], v[32:47]
	v_mfma_f32_32x32x16_bf16 v[16:31], v[68:71], v[174:177], v[16:31]
	v_mfma_f32_32x32x16_bf16 v[64:79], v[124:127], v[92:95], 0
	v_mfma_f32_32x32x16_bf16 v[64:79], v[132:135], v[88:91], v[64:79]
	v_mfma_f32_32x32x16_bf16 v[64:79], v[136:139], v[84:87], v[64:79]
	v_mfma_f32_32x32x16_bf16 v[64:79], v[140:143], v[80:83], v[64:79]
	s_cbranch_vccnz .LBB0_1926
	v_add_u32_e32 v136, 0x28988, v122
	v_add_u32_e32 v138, 0x289a0, v122
	v_add_u32_e32 v140, 0x289a8, v122
	v_add_u32_e32 v123, 0x289c0, v122
	v_add_u32_e32 v124, 0x289c8, v122
	v_add_u32_e32 v126, 0x289e0, v122
	v_add_u32_e32 v132, 0x289e8, v122
	v_add_u32_e32 v121, 0x28980, v122
	ds_read2_b32 v[122:123], v123 offset1:1
	ds_read2_b32 v[124:125], v124 offset1:1
	ds_read2_b32 v[126:127], v126 offset1:1
	ds_read2_b32 v[132:133], v132 offset1:1
	ds_read2_b32 v[134:135], v121 offset1:1
	ds_read2_b32 v[136:137], v136 offset1:1
	ds_read2_b32 v[138:139], v138 offset1:1
	ds_read2_b32 v[140:141], v140 offset1:1
	s_waitcnt lgkmcnt(0)
	v_pk_add_f32 v[78:79], v[78:79], v[132:133]
	v_pk_add_f32 v[76:77], v[76:77], v[126:127]
	v_pk_add_f32 v[74:75], v[74:75], v[124:125]
	v_pk_add_f32 v[72:73], v[72:73], v[122:123]
	v_pk_add_f32 v[70:71], v[70:71], v[140:141]
	v_pk_add_f32 v[68:69], v[68:69], v[138:139]
	v_pk_add_f32 v[66:67], v[66:67], v[136:137]
	v_pk_add_f32 v[64:65], v[64:65], v[134:135]

; DI int v_rd_base(int lane) { return ((lane & 3) << 3) | (((lane >> 2) & 3) << 6) | (((lane >> 4) & 1) << 5) | (((lane >> 5) & 1) << 8); }
; DI void expsum(f32x16& p, float& l_reg, bf16x8& pa0, bf16x8& pa1) {
; #pragma unroll
;     for (int r = 0; r < 16; ++r) p[r] = __builtin_amdgcn_exp2f(p[r]);
;     float ps = 0.f;
; #pragma unroll
;     for (int r = 0; r < 16; ++r) ps += p[r];
;     l_reg += ps; asm volatile("" : "+v"(l_reg));
;     ...
;     ATT_PK4(p, 0, pa0); ATT_PK4(p, 8, pa1);
; template <int DQK, int MODE, int LDQ, int LDK, int LDV> ...
;     ...
;     const int vbase = (int)(unsigned)(size_t)lds + V_OFF + v_rd_base(lane);
;     ...
;     constexpr int NDA = ND0 > 6 ? 6 : ND0;
.LBB0_1953:
	s_add_i32 s3, s0, -1
	s_add_i32 s2, s22, 0xffffa000
	s_and_b32 s2, s2, 0x6000
	v_add_u32_e32 v121, s2, v114
	v_add_u32_e32 v122, v121, v115
	v_add_u32_e32 v126, v121, v116
	ds_read_b128 v[122:125], v122 offset:4096
	ds_read_b128 v[132:135], v126 offset:4096
	v_add_u32_e32 v126, v121, v117
	v_add_u32_e32 v121, v121, v118
	s_lshl_b32 s2, s23, 14
	ds_read_b128 v[136:139], v126 offset:4096
	ds_read_b128 v[140:143], v121 offset:4096
	v_add_u32_e32 v121, s2, v106
	ds_read_b64_tr_b16 v[144:145], v121 offset:0
	ds_read_b64_tr_b16 v[146:147], v121 offset:0x800
	ds_read_b64_tr_b16 v[148:149], v121 offset:0x1000
	ds_read_b64_tr_b16 v[150:151], v121 offset:0x1800
	ds_read_b64_tr_b16 v[152:153], v121 offset:0x200
	ds_read_b64_tr_b16 v[154:155], v121 offset:0xa00
	ds_read_b64_tr_b16 v[156:157], v121 offset:0x1200
	ds_read_b64_tr_b16 v[158:159], v121 offset:0x1a00
	ds_read_b64_tr_b16 v[162:163], v121 offset:0x400
	ds_read_b64_tr_b16 v[164:165], v121 offset:0xc00
	ds_read_b64_tr_b16 v[166:167], v121 offset:0x1400
	ds_read_b64_tr_b16 v[168:169], v121 offset:0x1c00
	ds_read_b64_tr_b16 v[170:171], v121 offset:0x600
	ds_read_b64_tr_b16 v[172:173], v121 offset:0xe00
	ds_read_b64_tr_b16 v[174:175], v121 offset:0x1600
	ds_read_b64_tr_b16 v[176:177], v121 offset:0x1e00
	s_setprio 1
	v_exp_f32_e32 v64, v64
	v_exp_f32_e32 v65, v65
	v_exp_f32_e32 v66, v66
	v_exp_f32_e32 v67, v67
	v_exp_f32_e32 v68, v68
	v_add_f32_e32 v126, 0, v64
	v_exp_f32_e32 v69, v69
	v_add_f32_e32 v126, v65, v126
	v_exp_f32_e32 v70, v70
	v_add_f32_e32 v126, v66, v126
	v_exp_f32_e32 v71, v71
	v_add_f32_e32 v126, v67, v126
	v_exp_f32_e32 v72, v72
	v_add_f32_e32 v126, v68, v126
	v_exp_f32_e32 v73, v73
	v_add_f32_e32 v126, v69, v126
	v_exp_f32_e32 v74, v74
	v_add_f32_e32 v126, v70, v126
	v_exp_f32_e32 v75, v75
	v_add_f32_e32 v126, v71, v126
	v_exp_f32_e32 v76, v76
	v_add_f32_e32 v126, v72, v126
	v_exp_f32_e32 v77, v77
	v_add_f32_e32 v126, v73, v126
	v_exp_f32_e32 v78, v78
	v_add_f32_e32 v126, v74, v126
	v_exp_f32_e32 v79, v79
	v_add_f32_e32 v126, v75, v126
	v_add_f32_e32 v126, v76, v126
	v_add_f32_e32 v126, v77, v126
	v_add_f32_e32 v126, v78, v126
	v_add_f32_e32 v126, v79, v126
	v_add_f32_e32 v120, v126, v120
	v_cvt_pk_bf16_f32 v64, v64, v65
	v_cvt_pk_bf16_f32 v65, v66, v67
	v_cvt_pk_bf16_f32 v66, v68, v69
	v_cvt_pk_bf16_f32 v67, v70, v71
	v_cvt_pk_bf16_f32 v68, v72, v73
	v_cvt_pk_bf16_f32 v69, v74, v75
	v_cvt_pk_bf16_f32 v70, v76, v77
	v_cvt_pk_bf16_f32 v71, v78, v79
	s_nop 0
	v_permlane32_swap_b32_e32 v64, v66
	v_permlane32_swap_b32_e32 v65, v67
	v_permlane32_swap_b32_e32 v68, v70
	v_permlane32_swap_b32_e32 v69, v71
	s_waitcnt lgkmcnt(0)
	s_setprio 0
	v_mfma_f32_32x32x16_bf16 v[0:15], v[64:67], v[144:147], v[0:15]
	s_cmp_lt_i32 s3, s47
	s_cselect_b64 s[74:75], -1, 0
	s_cmp_ge_i32 s3, s52
	s_cselect_b64 s[90:91], -1, 0
	s_or_b64 s[74:75], s[74:75], s[90:91]
	s_and_b64 vcc, exec, s[74:75]
	v_mfma_f32_32x32x16_bf16 v[48:63], v[64:67], v[152:155], v[48:63]
	v_mfma_f32_32x32x16_bf16 v[16:31], v[64:67], v[162:165], v[16:31]
	v_mfma_f32_32x32x16_bf16 v[32:47], v[64:67], v[170:173], v[32:47]
	v_mfma_f32_32x32x16_bf16 v[0:15], v[68:71], v[148:151], v[0:15]
	v_mfma_f32_32x32x16_bf16 v[48:63], v[68:71], v[156:159], v[48:63]
	v_mfma_f32_32x32x16_bf16 v[16:31], v[68:71], v[166:169], v[16:31]
	v_mfma_f32_32x32x16_bf16 v[32:47], v[68:71], v[174:177], v[32:47]
	v_mfma_f32_32x32x16_bf16 v[64:79], v[122:125], v[92:95], 0
	v_mfma_f32_32x32x16_bf16 v[64:79], v[132:135], v[88:91], v[64:79]
	v_mfma_f32_32x32x16_bf16 v[64:79], v[136:139], v[84:87], v[64:79]
	v_mfma_f32_32x32x16_bf16 v[64:79], v[140:143], v[80:83], v[64:79]
	v_add_u32_e32 v122, s7, v119
	s_cbranch_vccnz .LBB0_1955
	v_add_u32_e32 v138, 0x28908, v122
	v_add_u32_e32 v140, 0x28920, v122
	v_add_u32_e32 v142, 0x28928, v122
	v_add_u32_e32 v124, 0x28940, v122
	v_add_u32_e32 v126, 0x28948, v122
	v_add_u32_e32 v132, 0x28960, v122
	v_add_u32_e32 v134, 0x28968, v122
	v_add_u32_e32 v123, 0x28900, v122
	ds_read2_b32 v[124:125], v124 offset1:1
	ds_read2_b32 v[126:127], v126 offset1:1
	ds_read2_b32 v[132:133], v132 offset1:1
	ds_read2_b32 v[134:135], v134 offset1:1
	ds_read2_b32 v[136:137], v123 offset1:1
	ds_read2_b32 v[138:139], v138 offset1:1
	ds_read2_b32 v[140:141], v140 offset1:1
	ds_read2_b32 v[142:143], v142 offset1:1
	s_waitcnt lgkmcnt(0)
	v_pk_add_f32 v[78:79], v[78:79], v[134:135]
	v_pk_add_f32 v[76:77], v[76:77], v[132:133]
	v_pk_add_f32 v[74:75], v[74:75], v[126:127]
	v_pk_add_f32 v[72:73], v[72:73], v[124:125]
	v_pk_add_f32 v[70:71], v[70:71], v[142:143]
	v_pk_add_f32 v[68:69], v[68:69], v[140:141]
	v_pk_add_f32 v[66:67], v[66:67], v[138:139]
	v_pk_add_f32 v[64:65], v[64:65], v[136:137]

; #define LAS __attribute__((address_space(3)))
; DI int v_rd_base(int lane) { return ((lane & 3) << 3) | (((lane >> 2) & 3) << 6) | (((lane >> 4) & 1) << 5) | (((lane >> 5) & 1) << 8); }
; DI void pv_mma(f32x16* o, const s16x4* vf, bf16x8 pa0, bf16x8 pa1) {
;     ...
; #pragma unroll
;     for (int d0 = 0; d0 < 4; ++d0) {
;         o[d0] = __builtin_amdgcn_mfma_f32_32x32x16_bf16(pa0, ATT_PK(vf[4 * d0], vf[4 * d0 + 1]), o[d0], 0, 0, 0);
;         o[d0] = __builtin_amdgcn_mfma_f32_32x32x16_bf16(pa1, ATT_PK(vf[4 * d0 + 2], vf[4 * d0 + 3]), o[d0], 0, 0, 0); }
;     ...
; }
; template <int DQK, int D0A, int D0B> DI void k_reads(bf16x8* kf, const LAS unsigned char* Ks, int half, int r32, int hi) {
; #pragma unroll
;     for (int d0 = D0A; d0 < D0B; ++d0) kf[d0 - D0A] = *(const LAS bf16x8*)(Ks + half * (32 * DQK * 2) + kswz<DQK>(r32, (d0 * 16 + hi * 8) * 2));
; }
; template <int D0A, int D0B> DI void qk_mma(f32x16& p, const bf16x8* kf, const bf16x8* qr) {
; #pragma unroll
;     for (int d0 = D0A; d0 < D0B; ++d0) {
;         if (d0 == 0) { f32x16 z; _Pragma("unroll") for (int r = 0; r < 16; ++r) z[r] = 0.f; p = __builtin_amdgcn_mfma_f32_32x32x16_bf16(kf[0], qr[0], z, 0, 0, 0); }
;         else p = __builtin_amdgcn_mfma_f32_32x32x16_bf16(kf[d0 - D0A], qr[d0], p, 0, 0, 0); }
; }
; template <int DQK, int MODE, int LDQ, int LDK, int LDV> ...
;     ...
;     const int vbase = (int)(unsigned)(size_t)lds + V_OFF + v_rd_base(lane);
;     ...
;     constexpr int NDA = ND0 > 6 ? 6 : ND0;
.Lstg_d1_mid_19:
	v_mfma_f32_32x32x16_bf16 v[0:15], v[64:67], v[144:147], v[0:15]
	s_cmp_lt_i32 s0, s47
	s_cselect_b64 s[74:75], -1, 0
	s_cmp_ge_i32 s0, s52
	s_cselect_b64 s[90:91], -1, 0
	s_or_b64 s[74:75], s[74:75], s[90:91]
	s_and_b64 vcc, exec, s[74:75]
	v_mfma_f32_32x32x16_bf16 v[48:63], v[64:67], v[152:155], v[48:63]
	v_mfma_f32_32x32x16_bf16 v[16:31], v[64:67], v[162:165], v[16:31]
	v_mfma_f32_32x32x16_bf16 v[32:47], v[64:67], v[170:173], v[32:47]
	v_mfma_f32_32x32x16_bf16 v[0:15], v[68:71], v[148:151], v[0:15]
	v_mfma_f32_32x32x16_bf16 v[48:63], v[68:71], v[156:159], v[48:63]
	v_mfma_f32_32x32x16_bf16 v[16:31], v[68:71], v[166:169], v[16:31]
	v_mfma_f32_32x32x16_bf16 v[32:47], v[68:71], v[174:177], v[32:47]
	v_mfma_f32_32x32x16_bf16 v[64:79], v[124:127], v[92:95], 0
	v_mfma_f32_32x32x16_bf16 v[64:79], v[132:135], v[88:91], v[64:79]
	v_mfma_f32_32x32x16_bf16 v[64:79], v[136:139], v[84:87], v[64:79]
	v_mfma_f32_32x32x16_bf16 v[64:79], v[140:143], v[80:83], v[64:79]
	s_cbranch_vccnz .LBB0_1957
	v_add_u32_e32 v136, 0x28988, v122
	v_add_u32_e32 v138, 0x289a0, v122
	v_add_u32_e32 v140, 0x289a8, v122
	v_add_u32_e32 v123, 0x289c0, v122
	v_add_u32_e32 v124, 0x289c8, v122
	v_add_u32_e32 v126, 0x289e0, v122
	v_add_u32_e32 v132, 0x289e8, v122
	v_add_u32_e32 v121, 0x28980, v122
	ds_read2_b32 v[122:123], v123 offset1:1
	ds_read2_b32 v[124:125], v124 offset1:1
	ds_read2_b32 v[126:127], v126 offset1:1
	ds_read2_b32 v[132:133], v132 offset1:1
	ds_read2_b32 v[134:135], v121 offset1:1
	ds_read2_b32 v[136:137], v136 offset1:1
	ds_read2_b32 v[138:139], v138 offset1:1
	ds_read2_b32 v[140:141], v140 offset1:1
	s_waitcnt lgkmcnt(0)
	v_pk_add_f32 v[78:79], v[78:79], v[132:133]
	v_pk_add_f32 v[76:77], v[76:77], v[126:127]
	v_pk_add_f32 v[74:75], v[74:75], v[124:125]
	v_pk_add_f32 v[72:73], v[72:73], v[122:123]
	v_pk_add_f32 v[70:71], v[70:71], v[140:141]
	v_pk_add_f32 v[68:69], v[68:69], v[138:139]
	v_pk_add_f32 v[66:67], v[66:67], v[136:137]
	v_pk_add_f32 v[64:65], v[64:65], v[134:135]

.Lstg_mla_top_2:
	s_mov_b32 m0, s1
	s_mov_b32 s0, s5
	s_mov_b32 s5, s44
	s_mov_b32 s44, s4
	s_lshl_b32 s4, s4, 14
	global_load_lds_dwordx4 v136, s[34:35]
	s_add_i32 m0, s1, 0x2000
	s_add_i32 s4, s52, s4
	global_load_lds_dwordx4 v138, s[34:35]
	s_add_i32 m0, s1, 0x4000
	s_add_i32 s6, s4, 0x400
	global_load_lds_dwordx4 v140, s[34:35]
	s_mov_b32 m0, s4
	s_add_i32 s1, s43, -3
	global_load_lds_dwordx4 v144, s[34:35]
	s_mov_b32 m0, s6
	s_nop 0
	global_load_lds_dwordx4 v142, s[34:35]
	s_and_b32 s1, s1, 3
	s_mulk_i32 s1, 0x6000
	v_add_u32_e32 v246, s1, v158
	v_add_u32_e32 v174, v246, v151
	v_add_u32_e32 v178, v246, v149
	v_add_u32_e32 v182, v246, v148
	v_add_u32_e32 v186, v246, v147
	v_add_u32_e32 v190, v246, v146
	v_add_u32_e32 v194, v246, v150
	s_lshl_b32 s1, s0, 14
	ds_read_b128 v[174:177], v174 offset:12288
	ds_read_b128 v[178:181], v178 offset:12288
	ds_read_b128 v[182:185], v182 offset:12288
	ds_read_b128 v[186:189], v186 offset:12288
	ds_read_b128 v[190:193], v190 offset:12288
	ds_read_b128 v[194:197], v194 offset:12288
	v_add_u32_e32 v254, s1, v130
	ds_read_b64_tr_b16 v[198:199], v254 offset:0
	ds_read_b64_tr_b16 v[200:201], v254 offset:0x800
	ds_read_b64_tr_b16 v[202:203], v254 offset:0x1000
	ds_read_b64_tr_b16 v[204:205], v254 offset:0x1800
	ds_read_b64_tr_b16 v[206:207], v254 offset:0x200
	ds_read_b64_tr_b16 v[208:209], v254 offset:0xa00
	ds_read_b64_tr_b16 v[210:211], v254 offset:0x1200
	ds_read_b64_tr_b16 v[212:213], v254 offset:0x1a00
	ds_read_b64_tr_b16 v[214:215], v254 offset:0x400
	ds_read_b64_tr_b16 v[216:217], v254 offset:0xc00
	ds_read_b64_tr_b16 v[218:219], v254 offset:0x1400
	ds_read_b64_tr_b16 v[220:221], v254 offset:0x1c00
	ds_read_b64_tr_b16 v[222:223], v254 offset:0x600
	ds_read_b64_tr_b16 v[224:225], v254 offset:0xe00
	ds_read_b64_tr_b16 v[226:227], v254 offset:0x1600
	ds_read_b64_tr_b16 v[228:229], v254 offset:0x1e00
	s_setprio 1
	v_exp_f32_e32 v64, v64
	v_exp_f32_e32 v65, v65
	v_exp_f32_e32 v66, v66
	v_exp_f32_e32 v67, v67
	v_exp_f32_e32 v68, v68
	v_add_f32_e32 v230, 0, v64
	v_exp_f32_e32 v69, v69
	v_add_f32_e32 v230, v65, v230
	v_exp_f32_e32 v70, v70
	v_add_f32_e32 v230, v66, v230
	v_exp_f32_e32 v71, v71
	v_add_f32_e32 v230, v67, v230
	v_exp_f32_e32 v72, v72
	v_add_f32_e32 v230, v68, v230
	v_exp_f32_e32 v73, v73
	v_add_f32_e32 v230, v69, v230
	v_exp_f32_e32 v74, v74
	v_add_f32_e32 v230, v70, v230
	v_exp_f32_e32 v75, v75
	v_add_f32_e32 v230, v71, v230
	v_exp_f32_e32 v76, v76
	v_add_f32_e32 v230, v72, v230
	v_exp_f32_e32 v77, v77
	v_add_f32_e32 v230, v73, v230
	v_exp_f32_e32 v78, v78
	v_add_f32_e32 v230, v74, v230
	v_exp_f32_e32 v79, v79
	v_add_f32_e32 v230, v75, v230
	v_add_f32_e32 v230, v76, v230
	v_add_f32_e32 v230, v77, v230
	v_add_f32_e32 v230, v78, v230
	v_add_f32_e32 v230, v79, v230
	v_add_f32_e32 v173, v173, v230
	v_cvt_pk_bf16_f32 v64, v64, v65
	v_cvt_pk_bf16_f32 v65, v66, v67
	v_cvt_pk_bf16_f32 v66, v68, v69
	v_cvt_pk_bf16_f32 v67, v70, v71
	v_cvt_pk_bf16_f32 v68, v72, v73
	v_cvt_pk_bf16_f32 v69, v74, v75
	v_cvt_pk_bf16_f32 v70, v76, v77
	v_cvt_pk_bf16_f32 v71, v78, v79
	s_nop 0
	v_permlane32_swap_b32_e32 v64, v66
	v_permlane32_swap_b32_e32 v65, v67
	v_permlane32_swap_b32_e32 v68, v70
	v_permlane32_swap_b32_e32 v69, v71
	s_waitcnt lgkmcnt(0)
	v_add_u32_e32 v72, v246, v152
	v_add_u32_e32 v73, v246, v153
	ds_read_b128 v[230:233], v72 offset:12288
	ds_read_b128 v[234:237], v73 offset:12288
	v_add_u32_e32 v72, v246, v154
	v_add_u32_e32 v73, v246, v155
	ds_read_b128 v[238:241], v72 offset:12288
	ds_read_b128 v[242:245], v73 offset:12288
	v_add_u32_e32 v72, v246, v156
	v_add_u32_e32 v73, v246, v157
	ds_read_b128 v[246:249], v72 offset:12288
	ds_read_b128 v[250:253], v73 offset:12288
	s_setprio 0
	v_mfma_f32_32x32x16_bf16 v[48:63], v[64:67], v[198:201], v[48:63]
	v_mfma_f32_32x32x16_bf16 v[32:47], v[64:67], v[206:209], v[32:47]
	v_mfma_f32_32x32x16_bf16 v[16:31], v[64:67], v[214:217], v[16:31]
	v_mfma_f32_32x32x16_bf16 v[0:15], v[64:67], v[222:225], v[0:15]
	v_mfma_f32_32x32x16_bf16 v[48:63], v[68:71], v[202:205], v[48:63]
	v_mfma_f32_32x32x16_bf16 v[32:47], v[68:71], v[210:213], v[32:47]
	v_mfma_f32_32x32x16_bf16 v[16:31], v[68:71], v[218:221], v[16:31]
	v_mfma_f32_32x32x16_bf16 v[0:15], v[68:71], v[226:229], v[0:15]
	s_waitcnt lgkmcnt(0)
; #define SBAR() __builtin_amdgcn_sched_barrier(0)
; #define ATT_DMA_K(t) do { const bf16_t* kg_ = Kh + (size_t)(t) * 64 * LDK; LAS unsigned char* sb_ = lds + ((t) & 3) * KBUF; \
;     _Pragma("unroll") for (int i_ = 0; i_ < NKP; ++i_) __builtin_amdgcn_global_load_lds((const unsigned*)(kg_ + kgo[i_]), (LAS unsigned*)(sb_ + (wid + 8 * i_) * 1024), 16, 0, 0); } while (0)
; #define ATT_DMA_V(t, vs) do { const bf16_t* vg_ = Vh + (size_t)(t) * 64 * LDV; LAS unsigned char* sb_ = lds + V_OFF + (vs) * SHM_V; \
;     _Pragma("unroll") for (int i_ = 0; i_ < 2; ++i_) __builtin_amdgcn_global_load_lds((const unsigned*)(vg_ + vgo[i_]), (LAS unsigned*)(sb_ + (2 * wid + i_) * 1024), 16, 0, 0); } while (0)
; #define ATT_SEG(t) do { if constexpr (MODE != 0) { if (((t) == tL && tL > 0) || (t) == tR) { const float f_ = (t) == tR ? fR : fL; l_reg *= f_; \
;     _Pragma("unroll") for (int d = 0; d < 4; ++d) _Pragma("unroll") for (int r = 0; r < 16; ++r) o[d][r] *= f_; } } } while (0)
; #define ATT_TOP(N) do { asm volatile("s_waitcnt vmcnt(%0)" :: "n"(N) : "memory"); __builtin_amdgcn_s_barrier(); asm volatile("" ::: "memory"); } while (0)
; template <int DQK, int MODE, int LDQ, int LDK, int LDV> ...
;     ...
;     for (int j = 0; j < NT; ++j) {
;         if (j + 2 < NT) ATT_TOP(NKP + 2); else ATT_TOP(0);
;         if (j + 3 < NT) ATT_DMA_K(j + 3);
;         if (j + 2 < NT) ATT_DMA_V(j + 2, v2);
;         ATT_SEG(j); SBAR();
;         ATT_STEP(pA, pB, 0, v0, true, 1, j);
;         ATT_STEP(pB, pA, 1, v0, (j + 1 < NT), 0, j + 1);
;         { const int t_ = v0; v0 = v1; v1 = v2; v2 = t_; }
	v_mfma_f32_32x32x16_bf16 v[64:79], v[174:177], v[80:83], 0
	v_mfma_f32_32x32x16_bf16 v[64:79], v[178:181], v[84:87], v[64:79]
	v_mfma_f32_32x32x16_bf16 v[64:79], v[182:185], v[88:91], v[64:79]
	v_mfma_f32_32x32x16_bf16 v[64:79], v[186:189], v[92:95], v[64:79]
	v_mfma_f32_32x32x16_bf16 v[64:79], v[190:193], v[96:99], v[64:79]
	v_mfma_f32_32x32x16_bf16 v[64:79], v[194:197], v[100:103], v[64:79]
	v_mfma_f32_32x32x16_bf16 v[64:79], v[230:233], v[104:107], v[64:79]
	v_mfma_f32_32x32x16_bf16 v[64:79], v[234:237], v[108:111], v[64:79]
	v_mfma_f32_32x32x16_bf16 v[64:79], v[238:241], v[112:115], v[64:79]
	v_mfma_f32_32x32x16_bf16 v[64:79], v[242:245], v[116:119], v[64:79]
	v_mfma_f32_32x32x16_bf16 v[64:79], v[246:249], v[120:123], v[64:79]
	v_mfma_f32_32x32x16_bf16 v[64:79], v[250:253], v[124:127], v[64:79]
	s_add_i32 s4, s43, -2
	s_and_b32 s4, s4, 3
	s_mulk_i32 s4, 0x6000
	v_add_u32_e32 v246, s4, v158
	v_add_u32_e32 v174, v246, v151
	v_add_u32_e32 v178, v246, v149
	v_add_u32_e32 v182, v246, v148
	v_add_u32_e32 v186, v246, v147
	v_add_u32_e32 v190, v246, v146
	v_add_u32_e32 v194, v246, v150
	ds_read_b128 v[174:177], v174
	ds_read_b128 v[178:181], v178
	ds_read_b128 v[182:185], v182
	ds_read_b128 v[186:189], v186
	ds_read_b128 v[190:193], v190
	ds_read_b128 v[194:197], v194
	ds_read_b64_tr_b16 v[198:199], v254 offset:0x2000
	ds_read_b64_tr_b16 v[200:201], v254 offset:0x2800
	ds_read_b64_tr_b16 v[202:203], v254 offset:0x3000
	ds_read_b64_tr_b16 v[204:205], v254 offset:0x3800
	ds_read_b64_tr_b16 v[206:207], v254 offset:0x2200
	ds_read_b64_tr_b16 v[208:209], v254 offset:0x2a00
	ds_read_b64_tr_b16 v[210:211], v254 offset:0x3200
	ds_read_b64_tr_b16 v[212:213], v254 offset:0x3a00
	ds_read_b64_tr_b16 v[214:215], v254 offset:0x2400
	ds_read_b64_tr_b16 v[216:217], v254 offset:0x2c00
	ds_read_b64_tr_b16 v[218:219], v254 offset:0x3400
	ds_read_b64_tr_b16 v[220:221], v254 offset:0x3c00
	ds_read_b64_tr_b16 v[222:223], v254 offset:0x2600
	ds_read_b64_tr_b16 v[224:225], v254 offset:0x2e00
	ds_read_b64_tr_b16 v[226:227], v254 offset:0x3600
	ds_read_b64_tr_b16 v[228:229], v254 offset:0x3e00
	s_setprio 1
	v_exp_f32_e32 v64, v64
	v_exp_f32_e32 v65, v65
	v_exp_f32_e32 v66, v66
	v_exp_f32_e32 v67, v67
	v_exp_f32_e32 v68, v68
	v_add_f32_e32 v230, 0, v64
	v_exp_f32_e32 v69, v69
	v_add_f32_e32 v230, v65, v230
	v_exp_f32_e32 v70, v70
	v_add_f32_e32 v230, v66, v230
	v_exp_f32_e32 v71, v71
	v_add_f32_e32 v230, v67, v230
	v_exp_f32_e32 v72, v72
	v_add_f32_e32 v230, v68, v230
	v_exp_f32_e32 v73, v73
	v_add_f32_e32 v230, v69, v230
	v_exp_f32_e32 v74, v74
	v_add_f32_e32 v230, v70, v230
	v_exp_f32_e32 v75, v75
	v_add_f32_e32 v230, v71, v230
	v_exp_f32_e32 v76, v76
	v_add_f32_e32 v230, v72, v230
	v_exp_f32_e32 v77, v77
	v_add_f32_e32 v230, v73, v230
	v_exp_f32_e32 v78, v78
	v_add_f32_e32 v230, v74, v230
	v_exp_f32_e32 v79, v79
	v_add_f32_e32 v230, v75, v230
	v_add_f32_e32 v230, v76, v230
	v_add_f32_e32 v230, v77, v230
	v_add_f32_e32 v230, v78, v230
	v_add_f32_e32 v230, v79, v230
	v_add_f32_e32 v173, v173, v230
	v_cvt_pk_bf16_f32 v64, v64, v65
	v_cvt_pk_bf16_f32 v65, v66, v67
	v_cvt_pk_bf16_f32 v66, v68, v69
	v_cvt_pk_bf16_f32 v67, v70, v71
	v_cvt_pk_bf16_f32 v68, v72, v73
	v_cvt_pk_bf16_f32 v69, v74, v75
	v_cvt_pk_bf16_f32 v70, v76, v77
	v_cvt_pk_bf16_f32 v71, v78, v79
	s_nop 0
	v_permlane32_swap_b32_e32 v64, v66
	v_permlane32_swap_b32_e32 v65, v67
	v_permlane32_swap_b32_e32 v68, v70
	v_permlane32_swap_b32_e32 v69, v71
	s_waitcnt lgkmcnt(0)
	v_add_u32_e32 v72, v246, v152
	v_add_u32_e32 v73, v246, v153
	ds_read_b128 v[230:233], v72
	ds_read_b128 v[234:237], v73
	v_add_u32_e32 v72, v246, v154
	v_add_u32_e32 v73, v246, v155
	ds_read_b128 v[238:241], v72
	ds_read_b128 v[242:245], v73
	v_add_u32_e32 v72, v246, v156
	v_add_u32_e32 v73, v246, v157
	ds_read_b128 v[246:249], v72
	ds_read_b128 v[250:253], v73
	s_setprio 0
	s_cmp_lt_u32 s33, 0x100
	s_cbranch_scc1 .Lstg_mla_mid_3
	s_waitcnt vmcnt(5)
	s_barrier
.Lstg_mla_mid_3:
	v_mfma_f32_32x32x16_bf16 v[48:63], v[64:67], v[198:201], v[48:63]
	v_mfma_f32_32x32x16_bf16 v[32:47], v[64:67], v[206:209], v[32:47]
	v_mfma_f32_32x32x16_bf16 v[16:31], v[64:67], v[214:217], v[16:31]
	v_mfma_f32_32x32x16_bf16 v[0:15], v[64:67], v[222:225], v[0:15]
	v_mfma_f32_32x32x16_bf16 v[48:63], v[68:71], v[202:205], v[48:63]
	v_mfma_f32_32x32x16_bf16 v[32:47], v[68:71], v[210:213], v[32:47]
	v_mfma_f32_32x32x16_bf16 v[16:31], v[68:71], v[218:221], v[16:31]
	v_mfma_f32_32x32x16_bf16 v[0:15], v[68:71], v[226:229], v[0:15]
	s_waitcnt lgkmcnt(0)
	v_mfma_f32_32x32x16_bf16 v[64:79], v[174:177], v[80:83], 0
	v_mfma_f32_32x32x16_bf16 v[64:79], v[178:181], v[84:87], v[64:79]
	v_mfma_f32_32x32x16_bf16 v[64:79], v[182:185], v[88:91], v[64:79]
	v_mfma_f32_32x32x16_bf16 v[64:79], v[186:189], v[92:95], v[64:79]
	v_mfma_f32_32x32x16_bf16 v[64:79], v[190:193], v[96:99], v[64:79]
	v_mfma_f32_32x32x16_bf16 v[64:79], v[194:197], v[100:103], v[64:79]
	v_mfma_f32_32x32x16_bf16 v[64:79], v[230:233], v[104:107], v[64:79]
	v_mfma_f32_32x32x16_bf16 v[64:79], v[234:237], v[108:111], v[64:79]
	v_mfma_f32_32x32x16_bf16 v[64:79], v[238:241], v[112:115], v[64:79]
	v_mfma_f32_32x32x16_bf16 v[64:79], v[242:245], v[116:119], v[64:79]
	v_mfma_f32_32x32x16_bf16 v[64:79], v[246:249], v[120:123], v[64:79]
	v_mfma_f32_32x32x16_bf16 v[64:79], v[250:253], v[124:127], v[64:79]
	s_add_i32 s43, s43, 1
	v_add_u32_e32 v136, s36, v136
	v_add_u32_e32 v138, s36, v138
	v_add_u32_e32 v140, s36, v140
	v_add_u32_e32 v142, s38, v142
	v_add_u32_e32 v144, s38, v144
	s_cmp_eq_u32 s43, 64
	s_mov_b32 s4, s0
	s_cbranch_scc0 .LBB0_1982
	s_lshl_b32 s0, s55, 2
	s_add_i32 s4, s0, 0
	s_add_i32 s6, s52, s1
	s_add_i32 s4, s4, 0x24000
	s_add_i32 s7, s6, 0x400
	s_add_u32 s0, s2, 0x3f0000
	s_addc_u32 s1, s3, 0
	s_cmp_lt_u32 s33, 0x100
	s_cbranch_scc0 .Lstg_mla_t61_4
	s_waitcnt vmcnt(5)
	s_barrier
